# NSA top-k: per-token 64-step rank loop replaced by an exact 32-step radix threshold search (same selection, ties to lower index); on top of v52
# speedup vs baseline: 1.0049x; 1.0049x over previous
; __device__ __forceinline__ float rdlane(float v, int l) { return __int_as_float(__builtin_amdgcn_readlane(__float_as_int(v), l)); }
; __device__ __forceinline__ void nsa_unit(Frame& F, int b, int g, int c) {
;     ...
;             if (c >= 16) {
;                 const bool cand = (lane >= 1) && (lane <= c - 2);
;                 const float v = cand ? impG[tl * 64 + lane] + impL[tl * 64 + lane] : -__builtin_inff();
;                 int rank = 0;
;                 for (int i = 0; i < 64; ++i) { const float vi = rdlane(v, i); rank += ((vi > v) || (vi == v && i < lane)) ? 1 : 0; }
;                 mk = __ballot(cand && rank < 13) | 1ull | (1ull << c) | (1ull << (c - 1));
.LBB0_869:
	s_or_b64 exec, exec, s[0:1]
	v_ashrrev_i32_e32 v3, 31, v2
	v_or_b32_e32 v3, 0x80000000, v3
	v_xor_b32_e32 v3, v2, v3
	s_mov_b32 s98, 0
	s_mov_b32 s99, 0x80000000
.Lrk_870:
	s_or_b32 s100, s98, s99
	v_cmp_le_u32_e32 vcc, s100, v3
	s_and_b64 s[0:1], vcc, s[8:9]
	s_bcnt1_i32_b64 s101, s[0:1]
	s_cmp_ge_u32 s101, 13
	s_cselect_b32 s98, s100, s98
	s_lshr_b32 s99, s99, 1
	s_cmp_lg_u32 s99, 0
	s_cbranch_scc1 .Lrk_870
	v_cmp_lt_u32_e32 vcc, s98, v3
	s_and_b64 s[0:1], vcc, s[8:9]
	s_bcnt1_i32_b64 s101, s[0:1]
	s_sub_i32 s99, 13, s101
	v_cmp_eq_u32_e32 vcc, s98, v3
	s_and_b64 vcc, vcc, s[8:9]
	s_nop 1
	v_mbcnt_lo_u32_b32 v4, vcc_lo, 0
	v_mbcnt_hi_u32_b32 v4, vcc_hi, v4
	v_cmp_gt_u32_e64 s[100:101], s99, v4
	s_and_b64 vcc, vcc, s[100:101]
	s_or_b64 vcc, vcc, s[0:1]
	s_or_b64 s[14:15], s[10:11], vcc
	s_or_b32 s14, s14, 1

; __device__ __forceinline__ float rdlane(float v, int l) { return __int_as_float(__builtin_amdgcn_readlane(__float_as_int(v), l)); }
; __device__ __forceinline__ void nsa_unit(Frame& F, int b, int g, int c) {
;     ...
;             if (c >= 16) {
;                 const bool cand = (lane >= 1) && (lane <= c - 2);
;                 const float v = cand ? impG[tl * 64 + lane] + impL[tl * 64 + lane] : -__builtin_inff();
;                 int rank = 0;
;                 for (int i = 0; i < 64; ++i) { const float vi = rdlane(v, i); rank += ((vi > v) || (vi == v && i < lane)) ? 1 : 0; }
;                 mk = __ballot(cand && rank < 13) | 1ull | (1ull << c) | (1ull << (c - 1));
.Lrk_878:
	s_or_b32 s100, s98, s99
	v_cmp_le_u32_e32 vcc, s100, v3
	s_and_b64 s[0:1], vcc, s[8:9]
	s_bcnt1_i32_b64 s101, s[0:1]
	s_cmp_ge_u32 s101, 13
	s_cselect_b32 s98, s100, s98
	s_lshr_b32 s99, s99, 1
	s_cmp_lg_u32 s99, 0
	s_cbranch_scc1 .Lrk_878
	v_cmp_lt_u32_e32 vcc, s98, v3
	s_and_b64 s[0:1], vcc, s[8:9]
	s_bcnt1_i32_b64 s101, s[0:1]
	s_sub_i32 s99, 13, s101
	v_cmp_eq_u32_e32 vcc, s98, v3
	s_and_b64 vcc, vcc, s[8:9]
	s_nop 1
	v_mbcnt_lo_u32_b32 v4, vcc_lo, 0
	v_mbcnt_hi_u32_b32 v4, vcc_hi, v4
	v_cmp_gt_u32_e64 s[100:101], s99, v4
	s_and_b64 vcc, vcc, s[100:101]
	s_or_b64 vcc, vcc, s[0:1]
	s_or_b64 s[16:17], s[10:11], vcc
	s_or_b32 s16, s16, 1

; __device__ __forceinline__ float rdlane(float v, int l) { return __int_as_float(__builtin_amdgcn_readlane(__float_as_int(v), l)); }
; __device__ __forceinline__ void nsa_unit(Frame& F, int b, int g, int c) {
;     ...
;             if (c >= 16) {
;                 const bool cand = (lane >= 1) && (lane <= c - 2);
;                 const float v = cand ? impG[tl * 64 + lane] + impL[tl * 64 + lane] : -__builtin_inff();
;                 int rank = 0;
;                 for (int i = 0; i < 64; ++i) { const float vi = rdlane(v, i); rank += ((vi > v) || (vi == v && i < lane)) ? 1 : 0; }
;                 mk = __ballot(cand && rank < 13) | 1ull | (1ull << c) | (1ull << (c - 1));
.Lrk_886:
	s_or_b32 s100, s98, s99
	v_cmp_le_u32_e32 vcc, s100, v3
	s_and_b64 s[0:1], vcc, s[8:9]
	s_bcnt1_i32_b64 s101, s[0:1]
	s_cmp_ge_u32 s101, 13
	s_cselect_b32 s98, s100, s98
	s_lshr_b32 s99, s99, 1
	s_cmp_lg_u32 s99, 0
	s_cbranch_scc1 .Lrk_886
	v_cmp_lt_u32_e32 vcc, s98, v3
	s_and_b64 s[0:1], vcc, s[8:9]
	s_bcnt1_i32_b64 s101, s[0:1]
	s_sub_i32 s99, 13, s101
	v_cmp_eq_u32_e32 vcc, s98, v3
	s_and_b64 vcc, vcc, s[8:9]
	s_nop 1
	v_mbcnt_lo_u32_b32 v4, vcc_lo, 0
	v_mbcnt_hi_u32_b32 v4, vcc_hi, v4
	v_cmp_gt_u32_e64 s[100:101], s99, v4
	s_and_b64 vcc, vcc, s[100:101]
	s_or_b64 vcc, vcc, s[0:1]
	s_or_b64 s[18:19], s[10:11], vcc
	s_or_b32 s18, s18, 1

; __device__ __forceinline__ float rdlane(float v, int l) { return __int_as_float(__builtin_amdgcn_readlane(__float_as_int(v), l)); }
; __device__ __forceinline__ void nsa_unit(Frame& F, int b, int g, int c) {
;     ...
;             if (c >= 16) {
;                 const bool cand = (lane >= 1) && (lane <= c - 2);
;                 const float v = cand ? impG[tl * 64 + lane] + impL[tl * 64 + lane] : -__builtin_inff();
;                 int rank = 0;
;                 for (int i = 0; i < 64; ++i) { const float vi = rdlane(v, i); rank += ((vi > v) || (vi == v && i < lane)) ? 1 : 0; }
;                 mk = __ballot(cand && rank < 13) | 1ull | (1ull << c) | (1ull << (c - 1));
.Lrk_894:
	s_or_b32 s100, s98, s99
	v_cmp_le_u32_e32 vcc, s100, v3
	s_and_b64 s[0:1], vcc, s[8:9]
	s_bcnt1_i32_b64 s101, s[0:1]
	s_cmp_ge_u32 s101, 13
	s_cselect_b32 s98, s100, s98
	s_lshr_b32 s99, s99, 1
	s_cmp_lg_u32 s99, 0
	s_cbranch_scc1 .Lrk_894
	v_cmp_lt_u32_e32 vcc, s98, v3
	s_and_b64 s[0:1], vcc, s[8:9]
	s_bcnt1_i32_b64 s101, s[0:1]
	s_sub_i32 s99, 13, s101
	v_cmp_eq_u32_e32 vcc, s98, v3
	s_and_b64 vcc, vcc, s[8:9]
	s_nop 1
	v_mbcnt_lo_u32_b32 v4, vcc_lo, 0
	v_mbcnt_hi_u32_b32 v4, vcc_hi, v4
	v_cmp_gt_u32_e64 s[100:101], s99, v4
	s_and_b64 vcc, vcc, s[100:101]
	s_or_b64 vcc, vcc, s[0:1]
	s_or_b64 s[20:21], s[10:11], vcc
	s_or_b32 s20, s20, 1

; __device__ __forceinline__ float rdlane(float v, int l) { return __int_as_float(__builtin_amdgcn_readlane(__float_as_int(v), l)); }
; __device__ __forceinline__ void nsa_unit(Frame& F, int b, int g, int c) {
;     ...
;             if (c >= 16) {
;                 const bool cand = (lane >= 1) && (lane <= c - 2);
;                 const float v = cand ? impG[tl * 64 + lane] + impL[tl * 64 + lane] : -__builtin_inff();
;                 int rank = 0;
;                 for (int i = 0; i < 64; ++i) { const float vi = rdlane(v, i); rank += ((vi > v) || (vi == v && i < lane)) ? 1 : 0; }
;                 mk = __ballot(cand && rank < 13) | 1ull | (1ull << c) | (1ull << (c - 1));
.Lrk_902:
	s_or_b32 s100, s98, s99
	v_cmp_le_u32_e32 vcc, s100, v3
	s_and_b64 s[0:1], vcc, s[8:9]
	s_bcnt1_i32_b64 s101, s[0:1]
	s_cmp_ge_u32 s101, 13
	s_cselect_b32 s98, s100, s98
	s_lshr_b32 s99, s99, 1
	s_cmp_lg_u32 s99, 0
	s_cbranch_scc1 .Lrk_902
	v_cmp_lt_u32_e32 vcc, s98, v3
	s_and_b64 s[0:1], vcc, s[8:9]
	s_bcnt1_i32_b64 s101, s[0:1]
	s_sub_i32 s99, 13, s101
	v_cmp_eq_u32_e32 vcc, s98, v3
	s_and_b64 vcc, vcc, s[8:9]
	s_nop 1
	v_mbcnt_lo_u32_b32 v4, vcc_lo, 0
	v_mbcnt_hi_u32_b32 v4, vcc_hi, v4
	v_cmp_gt_u32_e64 s[100:101], s99, v4
	s_and_b64 vcc, vcc, s[100:101]
	s_or_b64 vcc, vcc, s[0:1]
	s_or_b64 s[22:23], s[10:11], vcc
	s_or_b32 s22, s22, 1

; __device__ __forceinline__ float rdlane(float v, int l) { return __int_as_float(__builtin_amdgcn_readlane(__float_as_int(v), l)); }
; __device__ __forceinline__ void nsa_unit(Frame& F, int b, int g, int c) {
;     ...
;             if (c >= 16) {
;                 const bool cand = (lane >= 1) && (lane <= c - 2);
;                 const float v = cand ? impG[tl * 64 + lane] + impL[tl * 64 + lane] : -__builtin_inff();
;                 int rank = 0;
;                 for (int i = 0; i < 64; ++i) { const float vi = rdlane(v, i); rank += ((vi > v) || (vi == v && i < lane)) ? 1 : 0; }
;                 mk = __ballot(cand && rank < 13) | 1ull | (1ull << c) | (1ull << (c - 1));
.Lrk_910:
	s_or_b32 s100, s98, s99
	v_cmp_le_u32_e32 vcc, s100, v3
	s_and_b64 s[0:1], vcc, s[8:9]
	s_bcnt1_i32_b64 s101, s[0:1]
	s_cmp_ge_u32 s101, 13
	s_cselect_b32 s98, s100, s98
	s_lshr_b32 s99, s99, 1
	s_cmp_lg_u32 s99, 0
	s_cbranch_scc1 .Lrk_910
	v_cmp_lt_u32_e32 vcc, s98, v3
	s_and_b64 s[0:1], vcc, s[8:9]
	s_bcnt1_i32_b64 s101, s[0:1]
	s_sub_i32 s99, 13, s101
	v_cmp_eq_u32_e32 vcc, s98, v3
	s_and_b64 vcc, vcc, s[8:9]
	s_nop 1
	v_mbcnt_lo_u32_b32 v4, vcc_lo, 0
	v_mbcnt_hi_u32_b32 v4, vcc_hi, v4
	v_cmp_gt_u32_e64 s[100:101], s99, v4
	s_and_b64 vcc, vcc, s[100:101]
	s_or_b64 vcc, vcc, s[0:1]
	s_or_b64 s[24:25], s[10:11], vcc
	s_or_b32 s24, s24, 1

; __device__ __forceinline__ float rdlane(float v, int l) { return __int_as_float(__builtin_amdgcn_readlane(__float_as_int(v), l)); }
; __device__ __forceinline__ void nsa_unit(Frame& F, int b, int g, int c) {
;     ...
;             if (c >= 16) {
;                 const bool cand = (lane >= 1) && (lane <= c - 2);
;                 const float v = cand ? impG[tl * 64 + lane] + impL[tl * 64 + lane] : -__builtin_inff();
;                 int rank = 0;
;                 for (int i = 0; i < 64; ++i) { const float vi = rdlane(v, i); rank += ((vi > v) || (vi == v && i < lane)) ? 1 : 0; }
;                 mk = __ballot(cand && rank < 13) | 1ull | (1ull << c) | (1ull << (c - 1));
.Lrk_948:
	s_or_b32 s100, s98, s99
	v_cmp_le_u32_e32 vcc, s100, v3
	s_and_b64 s[0:1], vcc, s[8:9]
	s_bcnt1_i32_b64 s101, s[0:1]
	s_cmp_ge_u32 s101, 13
	s_cselect_b32 s98, s100, s98
	s_lshr_b32 s99, s99, 1
	s_cmp_lg_u32 s99, 0
	s_cbranch_scc1 .Lrk_948
	v_cmp_lt_u32_e32 vcc, s98, v3
	s_and_b64 s[0:1], vcc, s[8:9]
	s_bcnt1_i32_b64 s101, s[0:1]
	s_sub_i32 s99, 13, s101
	v_cmp_eq_u32_e32 vcc, s98, v3
	s_and_b64 vcc, vcc, s[8:9]
	s_nop 1
	v_mbcnt_lo_u32_b32 v4, vcc_lo, 0
	v_mbcnt_hi_u32_b32 v4, vcc_hi, v4
	v_cmp_gt_u32_e64 s[100:101], s99, v4
	s_and_b64 vcc, vcc, s[100:101]
	s_or_b64 vcc, vcc, s[0:1]
	s_or_b64 s[6:7], s[10:11], vcc
	s_or_b32 s6, s6, 1
	s_and_saveexec_b64 s[0:1], s[2:3]
	s_cbranch_execz .LBB0_916

; __device__ __forceinline__ float rdlane(float v, int l) { return __int_as_float(__builtin_amdgcn_readlane(__float_as_int(v), l)); }
; __device__ __forceinline__ void nsa_unit(Frame& F, int b, int g, int c) {
;     ...
;             if (c >= 16) {
;                 const bool cand = (lane >= 1) && (lane <= c - 2);
;                 const float v = cand ? impG[tl * 64 + lane] + impL[tl * 64 + lane] : -__builtin_inff();
;                 int rank = 0;
;                 for (int i = 0; i < 64; ++i) { const float vi = rdlane(v, i); rank += ((vi > v) || (vi == v && i < lane)) ? 1 : 0; }
;                 mk = __ballot(cand && rank < 13) | 1ull | (1ull << c) | (1ull << (c - 1));
.Lrk_954:
	s_or_b32 s100, s98, s99
	v_cmp_le_u32_e32 vcc, s100, v3
	s_and_b64 s[0:1], vcc, s[8:9]
	s_bcnt1_i32_b64 s101, s[0:1]
	s_cmp_ge_u32 s101, 13
	s_cselect_b32 s98, s100, s98
	s_lshr_b32 s99, s99, 1
	s_cmp_lg_u32 s99, 0
	s_cbranch_scc1 .Lrk_954
	v_cmp_lt_u32_e32 vcc, s98, v3
	s_and_b64 s[0:1], vcc, s[8:9]
	s_bcnt1_i32_b64 s101, s[0:1]
	s_sub_i32 s99, 13, s101
	v_cmp_eq_u32_e32 vcc, s98, v3
	s_and_b64 vcc, vcc, s[8:9]
	s_nop 1
	v_mbcnt_lo_u32_b32 v4, vcc_lo, 0
	v_mbcnt_hi_u32_b32 v4, vcc_hi, v4
	v_cmp_gt_u32_e64 s[100:101], s99, v4
	s_and_b64 vcc, vcc, s[100:101]
	s_or_b64 vcc, vcc, s[0:1]
	s_or_b64 s[12:13], s[10:11], vcc
	s_or_b32 s12, s12, 1
	s_and_saveexec_b64 s[0:1], s[2:3]
	s_cbranch_execnz .LBB0_918
	s_branch .LBB0_919
